# B-head: 6720 ffn2 weight-conversion items moved from phase A to idle WGs (>=172) at head of phase B
# speedup vs baseline: 1.0125x; 1.0017x over previous
; #define LAS __attribute__((address_space(3)))
; __global__ void __launch_bounds__(NWAVES * 64, 2) fwd(Args a) {
;     extern __shared__ __attribute__((aligned(16))) unsigned char lds_raw[];
;     LAS unsigned char* lds = (LAS unsigned char*)lds_raw;
;     volatile LAS unsigned* MISC = (volatile LAS unsigned*)(lds + MISC_OFF);
;     {
;         const int tid0 = threadIdx.x;
;         for (int u = tid0; u < (LDS_BYTES - LDSCTL_OFF) / 4; u += NWAVES * 64) ((LAS unsigned*)(lds + LDSCTL_OFF))[u] = 0u;
;         __syncthreads();
;         if (tid0 < 28) ((LAS unsigned long long*)(lds + PTAB_OFF))[tid0] = (unsigned long long)a.in[tid0];
;         __syncthreads();
_Z3fwd4Args:
	s_mov_b32 s101, 0
	v_lshl_add_u32 v1, v0, 2, 0
	v_add_u32_e32 v1, 0x20000, v1
	v_mov_b32_e32 v2, 0
	s_mov_b64 s[40:41], s[0:1]
	ds_write2st64_b32 v1, v2, v2 offset1:8
	ds_write2st64_b32 v1, v2, v2 offset0:16 offset1:24
	v_or_b32_e32 v1, 0x800, v0
	s_mov_b64 s[0:1], -1
	s_and_saveexec_b64 s[4:5], s[0:1]
	v_lshl_add_u32 v3, v1, 2, 0
	v_add_u32_e32 v3, 0x20000, v3
	ds_write_b32 v3, v2
	s_or_b64 exec, exec, s[4:5]
	s_and_saveexec_b64 s[4:5], s[0:1]
	s_add_i32 s0, 0, 0x20000
	v_lshl_add_u32 v1, v1, 2, s0
	v_mov_b32_e32 v2, 0
	ds_write_b32 v1, v2 offset:2048
	s_or_b64 exec, exec, s[4:5]
	v_or_b32_e32 v1, 0xc00, v0
	v_cmp_gt_u32_e64 s[0:1], 7, 6
	v_cmp_gt_u32_e64 s[6:7], 7, 5
	s_and_saveexec_b64 s[4:5], s[6:7]
	v_lshl_add_u32 v2, v1, 2, 0
	v_add_u32_e32 v2, 0x20000, v2
	v_mov_b32_e32 v3, 0
	ds_write_b32 v2, v3
	s_or_b64 exec, exec, s[4:5]
	s_and_saveexec_b64 s[4:5], s[0:1]
	s_add_i32 s0, 0, 0x20000
	v_lshl_add_u32 v1, v1, 2, s0
	v_mov_b32_e32 v2, 0
	ds_write_b32 v1, v2 offset:2048
	s_or_b64 exec, exec, s[4:5]
	v_cmp_gt_u32_e32 vcc, 28, v0
	s_waitcnt lgkmcnt(0)
	s_barrier
	s_and_saveexec_b64 s[0:1], vcc
	s_cbranch_execz .LBB0_10
	v_lshlrev_b32_e32 v1, 3, v0
	global_load_dwordx2 v[2:3], v1, s[40:41]
	v_add_u32_e32 v1, 0, v1
	v_add_u32_e32 v1, 0x20240, v1
	s_waitcnt vmcnt(0)
	ds_write_b64 v1, v[2:3]

; #define LAS __attribute__((address_space(3)))
; #define IN(i) in_ptr(lds, (i))
; __device__ __forceinline__ void cvt_item(gfp W, int N, bf16* WT, int Kd, int k0, int n0, int drow0, LAS float* scr, int lane, gfp gk) {
; #pragma unroll 8
;     for (int i = 0; i < 32; ++i) { const int kk = 2 * i + (lane >> 5); scr[kk * 33 + (lane & 31)] = W[(size_t)(k0 + kk) * N + n0 + (lane & 31)]; }
; __global__ void __launch_bounds__(NWAVES * 64, 2) fwd(Args a) {
;     ...
;             constexpr int I_FFN = (D / 64) * (FF / 32), I_DN = (FF / 64) * (D / 32), I_IN = (D / 64) * (NIN / 32), I_UQ = (512 / 64) * (1536 / 32), I_UKV = (512 / 64) * (2048 / 32), I_BR = (1024 / 64) * (D / 32), I_O = (D / 64) * (D / 32);
;             constexpr int NITEMS = 4 * I_FFN + 2 * I_DN + I_IN + I_UQ + I_UKV + 3 * I_BR + I_O;
;             for (int rep = 0; rep < REP_CONV; ++rep)
;             for (int it = gw; it < NITEMS; it += NGW) {
;                 int r = it;
;                 if (r < I_FFN) { cvt_gu(IN(I_F1G) + (size_t)l * D * FF, (bf16*)(ws + W_GU1), 0, r, scr, lane, IN(I_F1N) + l * D); continue; } r -= I_FFN;
.LBB0_105:
	v_mov_b32_e32 v0, v1
	v_readlane_b32 s0, v248, 5
	v_mbcnt_lo_u32_b32 v0, -1, v0
	v_mbcnt_hi_u32_b32 v0, -1, v0
	v_add_u32_e32 v13, s0, v0
	v_readlane_b32 s10, v248, 10
	v_readfirstlane_b32 s0, v13
	s_ashr_i32 s28, s0, 6
	v_readlane_b32 s0, v248, 6
	s_add_i32 s29, s28, s0
	v_and_b32_e32 v15, 63, v0
	v_readlane_b32 s11, v248, 11
	s_cmp_eq_u32 s101, 0
	s_cbranch_scc1 .Lhd_init1
	s_cmp_eq_u32 s101, 1
	s_cbranch_scc0 .Lhd_init3
	s_add_i32 s29, s29, 9888
	s_branch .Lhd_initdone
.Lhd_init3:
	s_add_i32 s29, s29, 26784
	s_branch .Lhd_initdone
.Lhd_init1:
	s_mov_b32 s100, s29
.Lhd_initdone:
	s_cmp_gt_i32 s29, 0xc8bf
	s_cbranch_scc1 .LBB0_203
	v_and_b32_e32 v2, 31, v0
	v_and_b32_e32 v0, 7, v0
	v_lshlrev_b32_e32 v14, 3, v0
	v_mul_u32_u24_e32 v3, 0x420, v0
	v_lshlrev_b32_e32 v0, 4, v0
	v_lshl_add_u64 v[4:5], s[10:11], 0, v[0:1]
	s_mov_b64 s[14:15], 0xb900000
	v_lshl_add_u64 v[24:25], v[4:5], 0, s[14:15]
	s_mov_b64 s[14:15], 0x3100000
	s_lshl_b32 s0, s28, 14
	v_lshrrev_b32_e32 v40, 3, v15
	v_lshl_add_u64 v[26:27], v[4:5], 0, s[14:15]
	s_mov_b64 s[14:15], 0x7700000
	s_add_i32 s6, s0, 0
	v_lshlrev_b32_e32 v0, 2, v40
	v_lshl_add_u64 v[28:29], v[4:5], 0, s[14:15]
	s_mov_b64 s[14:15], 0x7500000
	v_lshl_add_u32 v12, v2, 2, s6
	v_add3_u32 v41, s6, v3, v0
	s_mov_b64 s[6:7], 0x8100000
	v_lshl_add_u64 v[30:31], v[4:5], 0, s[14:15]
	s_mov_b64 s[14:15], 0x4700000
	v_readlane_b32 s12, v247, 45
	v_lshl_add_u64 v[18:19], v[4:5], 0, s[6:7]
	s_mov_b64 s[6:7], 0x7d00000
	v_lshl_add_u64 v[32:33], v[4:5], 0, s[14:15]
	s_mov_b64 s[14:15], 0x8d00000
	s_lshl_b32 s0, s12, 22
	v_lshrrev_b32_e32 v10, 5, v15
	s_mov_b64 s[4:5], 0x8500000
	v_lshl_add_u64 v[20:21], v[4:5], 0, s[6:7]
	s_mov_b64 s[6:7], 0x7900000
	s_lshl_b32 s16, s12, 20
	s_mov_b32 s17, s1
	s_mul_i32 s18, s12, 0xc0000
	s_mov_b32 s19, s1
	s_mul_i32 s20, s12, 0x16a0000
	s_mov_b32 s21, s1
	v_lshl_add_u64 v[34:35], v[4:5], 0, s[14:15]
	s_mov_b64 s[14:15], 0x500000
	v_lshl_add_u64 v[16:17], v[4:5], 0, s[4:5]
	v_or_b32_e32 v42, 8, v40
	v_or_b32_e32 v43, 16, v40
	v_or_b32_e32 v44, 24, v40
	s_lshl_b32 s4, s12, 21
	s_mov_b32 s5, s1
	v_lshl_add_u64 v[22:23], v[4:5], 0, s[6:7]
	s_lshl_b32 s6, s12, 9
	s_mov_b32 s7, s1
	s_lshl_b32 s8, s12, 11
	s_mov_b32 s9, s1
	s_mul_i32 s12, s12, 0xb00000
	s_mov_b32 s13, s1
	v_lshl_add_u64 v[36:37], v[4:5], 0, s[14:15]
	v_mov_b32_e32 v11, v10
	s_lshl_b64 s[14:15], s[0:1], 2
	s_lshl_b64 s[16:17], s[16:17], 2
	s_lshl_b64 s[18:19], s[18:19], 2
	s_lshl_b64 s[20:21], s[20:21], 2
	v_lshlrev_b32_e32 v38, 2, v2
	s_branch .LBB0_110

; __global__ void __launch_bounds__(NWAVES * 64, 2) fwd(Args a) {
;     ...
;             for (int it = gw; it < NITEMS; it += NGW) {
.LBB0_109:
	s_cmp_eq_u32 s101, 0
	s_cbranch_scc0 .Lhd_latch23
	s_add_i32 s100, s100, s64
	s_cmp_gt_i32 s100, 44671
	s_cbranch_scc1 .LBB0_203
	s_mov_b32 s29, s100
	s_cmp_lt_i32 s100, 11264
	s_cbranch_scc1 .LBB0_110
	s_add_i32 s29, s29, 6720
	s_cmp_lt_i32 s100, 21440
	s_cbranch_scc1 .LBB0_110
	s_add_i32 s29, s29, 0
	s_branch .LBB0_110
.Lhd_latch23:
	s_add_i32 s29, s29, 672
	s_cmp_eq_u32 s101, 1
	s_cbranch_scc0 .Lhd_latch3
	s_cmp_gt_i32 s29, 17983
	s_cbranch_scc1 .LBB0_203
	s_branch .LBB0_110
.Lhd_latch3:
	s_cmp_gt_i32 s29, 28159
	s_cbranch_scc1 .LBB0_203

; __global__ void __launch_bounds__(NWAVES * 64, 2) fwd(Args a) {
;     ...
;             for (int rep = 0; rep < REP_CONV; ++rep)
;             for (int it = gw; it < NITEMS; it += NGW) {
.LBB0_203:
	s_cmp_eq_u32 s101, 0
	s_cbranch_scc1 .Lhd_203cont
	s_cmp_eq_u32 s101, 1
	s_cbranch_scc1 .Lhd_ret2
	s_branch .Lhd_ret2

; template <class Epi, class Sched, bool ALIGN_EPI = false, bool SP2 = false>
; __device__ __forceinline__ void gemm_phase(PG8_LAS unsigned char* lds, const Gemm g, const Sched& S, const Epi& E, int tid_in) {
;     int tid_ = tid_in; asm volatile("" : "+v"(tid_));
;     const int tid = tid_, wid = __builtin_amdgcn_readfirstlane(tid >> 6), lane = tid & 63, wr = wid >> 2, wc = wid & 3, fr = lane & 15, fq = lane >> 4;
;     const int K = g.K, LDA = g.lda;
;     unsigned voffA[2], voffB[2];
; #pragma unroll
;     for (int i = 0; i < 2; ++i) { int R, C; stage_rc(tid * 16 + i * 8192, R, C); const int Rb = Epi::PERM ? ((R & ~31) + perm32(R & 31)) : R;
;         voffA[i] = (unsigned)(R * LDA + C) * 2u; voffB[i] = (unsigned)(Rb * K + C) * 2u; }
;     const size_t kstep = (size_t)(BK * 2);
;     const size_t hstep = (size_t)HALF * K * 2, hstepA = (size_t)HALF * LDA * 2;
;     const size_t tstep = 2 * hstep;
;     const unsigned ldsw = (unsigned)wid * 1024u;
;     const int aoff = lds_byte(wr * 64 + fr, fq * 8), boff = lds_byte(wc * 32 + fr, fq * 8);
;     ...
;     Unit cur, nxt; int ui = 0;
;     if (!S.next(0, cur)) return;
;     f32x4 acc[2][2][4][2];
; #pragma unroll
;     for (int a = 0; a < 2; ++a)
; #pragma unroll
;         for (int b = 0; b < 2; ++b)
; #pragma unroll
;             for (int m = 0; m < 4; ++m)
; #pragma unroll
;                 for (int n = 0; n < 2; ++n) acc[a][b][m][n] = (f32x4){0.f, 0.f, 0.f, 0.f};
;     bf16x8 At[4][2], B0[2][2], B1[2][2];
;     const char* cA = cur.a; const char* cB = cur.b;
;     S.a_ready(cur);
;     if constexpr (SP2) {
;         PG8_STAGE(PG8_SB(0, 0), cB, voffB); PG8_STAGE(PG8_SB(0, 1), cB + hstep, voffB); PG8_STAGE(PG8_SA(0, 0), cA, voffA); PG8_STAGE(PG8_SA(0, 1), cA + hstepA, voffA);
;         if (wr == 1) PG8_BAR;
;         PG8_WAIT_V(2); PG8_BAR;
;         PG8_STAGE(PG8_SB(1, 0), cB + kstep, voffB); PG8_STAGE(PG8_SA(1, 0), cA + kstep, voffA); PG8_STAGE(PG8_SB(1, 1), cB + hstep + kstep, voffB);
;         PG8_WAIT_V(6); PG8_BAR;
;     } else {
; __global__ void __launch_bounds__(NWAVES * 64, 2) fwd(Args a) {
;     ...
;         { PHASE_VARS pg8::Gemm g{HN, (const bf16*)(ws + W_GU1), M, NGU, D, D}; pg8::StaticOrder S; S.init(g, G, (int)blockIdx.x); pg8::EpiSwiglu E{ACT, FF, RS + (size_t)(l * 3) * M};
;           pg8::gemm_phase<pg8::EpiSwiglu, pg8::StaticOrder, true, true>(lds, g, S, E, tid); }
.LBB0_269:
	s_waitcnt lgkmcnt(0)
	v_mov_b32_e32 v0, v1
	s_barrier
	s_cmp_lt_u32 s2, 172
	s_cbranch_scc1 .Lhd_skip2
	v_writelane_b32 v249, s18, 0
	v_writelane_b32 v249, s19, 1
	v_writelane_b32 v249, s20, 2
	v_writelane_b32 v249, s21, 3
	v_writelane_b32 v249, s22, 4
	v_writelane_b32 v249, s23, 5
	v_writelane_b32 v249, s24, 6
	v_writelane_b32 v249, s25, 7
	v_writelane_b32 v249, s40, 8
	v_mov_b32_e32 v250, v4
	s_mov_b32 s101, 1
	s_branch .LBB0_105
.Lhd_ret2:
	s_mov_b32 s101, 0
	v_readlane_b32 s18, v249, 0
	v_readlane_b32 s19, v249, 1
	v_readlane_b32 s20, v249, 2
	v_readlane_b32 s21, v249, 3
	v_readlane_b32 s22, v249, 4
	v_readlane_b32 s23, v249, 5
	v_readlane_b32 s24, v249, 6
	v_readlane_b32 s25, v249, 7
	v_readlane_b32 s40, v249, 8
	v_mov_b32_e32 v4, v250
	s_waitcnt lgkmcnt(0)
	s_barrier
	v_mov_b32_e32 v0, v1
.Lhd_skip2:
	v_readlane_b32 s4, v248, 14
	v_mbcnt_lo_u32_b32 v0, -1, v0
	v_mbcnt_hi_u32_b32 v0, -1, v0
	v_readlane_b32 s0, v248, 5
	v_readlane_b32 s5, v248, 15
	v_readlane_b32 s10, v248, 10
	v_add_u32_e32 v10, s0, v0
	v_cndmask_b32_e64 v0, 0, 1, s[4:5]
	v_readlane_b32 s11, v248, 11
	v_cmp_ne_u32_e64 s[6:7], 1, v0
	s_andn2_b64 vcc, exec, s[4:5]
	v_readfirstlane_b32 s12, v10
	v_writelane_b32 v246, s6, 9
	s_nop 1
	v_writelane_b32 v246, s7, 10
	s_cbranch_vccnz .LBB0_289
	v_lshlrev_b32_e32 v0, 4, v10
	v_add_u32_e32 v2, 0x2000, v0
	v_ashrrev_i32_e32 v3, 31, v2
	v_lshrrev_b32_e32 v3, 22, v3
	v_add_u32_e32 v3, v2, v3
	v_ashrrev_i32_e32 v11, 10, v3
	v_mul_i32_i24_e32 v3, 0x400, v11
	v_sub_u32_e32 v2, v2, v3
	v_lshrrev_b32_e32 v3, 4, v2
	v_bitop3_b32 v2, v3, v2, 32 bitop3:0x6c
	v_ashrrev_i32_e32 v3, 31, v2
	v_lshrrev_b32_e32 v3, 26, v3
	v_add_u32_e32 v3, v2, v3
	v_lshlrev_b32_e32 v4, 3, v11
	v_ashrrev_i32_e32 v12, 6, v3
	v_and_b32_e32 v4, -16, v4
	v_add_u32_e32 v4, v12, v4
	v_and_b32_e32 v5, 3, v12
	s_mov_b32 s6, 0xfffe0
	v_lshrrev_b32_e32 v6, 2, v4
	v_lshlrev_b32_e32 v7, 1, v4
	v_and_b32_e32 v3, 0xc0, v3
	v_and_or_b32 v5, v4, s6, v5
	v_and_b32_e32 v6, 4, v6
	v_and_b32_e32 v7, 24, v7
	v_sub_u32_e32 v2, v2, v3
	v_or3_b32 v5, v5, v6, v7
	v_lshlrev_b32_e32 v6, 5, v11
	v_ashrrev_i16_sdwa v2, v232, sext(v2) dst_sel:DWORD dst_unused:UNUSED_PAD src0_sel:DWORD src1_sel:BYTE_0
	v_and_b32_e32 v6, 32, v6
	v_bfe_i32 v13, v2, 0, 16
	v_add_lshl_u32 v2, v6, v13, 1
	v_lshl_add_u32 v130, v5, 12, v2
	v_lshl_add_u32 v132, v4, 12, v2
	v_bfe_i32 v2, v10, 27, 1
	v_lshrrev_b32_e32 v2, 22, v2
	v_add_u32_e32 v2, v0, v2
	v_and_b32_e32 v2, 0xfffffc00, v2
	v_sub_u32_e32 v0, v0, v2
	v_lshrrev_b32_e32 v2, 4, v0
	v_ashrrev_i32_e32 v3, 31, v10
	v_bitop3_b32 v0, v2, v0, 32 bitop3:0x6c
	v_lshrrev_b32_e32 v3, 26, v3
	v_ashrrev_i32_e32 v2, 31, v0
	v_add_u32_e32 v3, v10, v3
	s_add_u32 s0, s10, 0x11200000
	v_lshrrev_b32_e32 v2, 26, v2
	v_ashrrev_i32_e32 v15, 6, v3
	s_addc_u32 s4, s11, 0
	v_add_u32_e32 v2, v0, v2
	v_lshlrev_b32_e32 v3, 3, v15
	s_add_u32 s5, s10, 0x500000
	v_ashrrev_i32_e32 v14, 6, v2
	v_and_b32_e32 v3, -16, v3
	s_addc_u32 s30, s11, 0
	s_ashr_i32 s13, s12, 6
	v_add_u32_e32 v3, v14, v3
	v_and_b32_e32 v4, 3, v14
	s_ashr_i32 s14, s12, 8
	s_lshl_b32 s31, s13, 10
	v_and_or_b32 v4, v3, s6, v4
	v_lshrrev_b32_e32 v5, 2, v3
	v_lshlrev_b32_e32 v6, 1, v3
	v_and_b32_e32 v2, 0xc0, v2
	v_readlane_b32 s6, v248, 50
	v_and_b32_e32 v5, 4, v5
	v_and_b32_e32 v6, 24, v6
	v_sub_u32_e32 v0, v0, v2
	v_readlane_b32 s7, v248, 51
	s_add_u32 s24, s0, s6
	v_or3_b32 v4, v4, v5, v6
	v_lshlrev_b32_e32 v5, 5, v15
	v_ashrrev_i16_sdwa v0, v232, sext(v0) dst_sel:DWORD dst_unused:UNUSED_PAD src0_sel:DWORD src1_sel:BYTE_0
	s_addc_u32 s25, s4, s7
	v_readlane_b32 s6, v248, 52
	v_and_b32_e32 v5, 32, v5
	v_bfe_i32 v16, v0, 0, 16
	v_readlane_b32 s7, v248, 53
	s_add_u32 s26, s5, s6
	v_add_lshl_u32 v2, v5, v16, 1
	s_addc_u32 s27, s30, s7
	s_add_i32 s33, s31, 0
	v_lshl_add_u32 v0, v4, 12, v2
	s_add_i32 m0, s33, 0x10000
	v_lshl_add_u32 v134, v3, 12, v2
	global_load_lds_dwordx4 v0, s[26:27]
	s_add_i32 m0, s33, 0x12000
	s_add_u32 s6, s26, 0x80000
	global_load_lds_dwordx4 v130, s[26:27]
	s_addc_u32 s7, s27, 0
	s_add_i32 m0, s33, 0x14000
	s_add_i32 s34, s33, 0x2000
	global_load_lds_dwordx4 v0, s[6:7]
	s_add_i32 m0, s33, 0x16000
	v_mov_b32_e32 v131, v1
	global_load_lds_dwordx4 v130, s[6:7]
	s_mov_b32 m0, s33
	s_add_u32 s6, s24, 0x80000
	global_load_lds_dwordx4 v134, s[24:25]
	s_mov_b32 m0, s34
	s_addc_u32 s7, s25, 0
	s_add_i32 s35, s33, 0x4000
	global_load_lds_dwordx4 v132, s[24:25]
	s_mov_b32 m0, s35
	s_add_i32 s36, s33, 0x6000
	global_load_lds_dwordx4 v134, s[6:7]
	s_mov_b32 m0, s36
	v_mov_b32_e32 v135, v1
	global_load_lds_dwordx4 v132, s[6:7]
	v_mov_b32_e32 v133, v1
	s_cmp_eq_u32 s14, 1
	v_lshl_add_u64 v[8:9], s[26:27], 0, v[0:1]
	v_lshl_add_u64 v[6:7], s[26:27], 0, v[130:131]
	v_lshl_add_u64 v[2:3], s[24:25], 0, v[134:135]
	s_cselect_b64 s[6:7], -1, 0
	s_cmp_lg_u32 s14, 1
	v_lshl_add_u64 v[4:5], s[24:25], 0, v[132:133]
	s_cbranch_scc1 .LBB0_272
	s_barrier

; __global__ void __launch_bounds__(NWAVES * 64, 2) fwd(Args a) {
	.amdhsa_kernel _Z3fwd4Args
		.amdhsa_group_segment_fixed_size 0
		.amdhsa_private_segment_fixed_size 0
		.amdhsa_kernarg_size 496
		.amdhsa_user_sgpr_count 2
		.amdhsa_user_sgpr_dispatch_ptr 0
		.amdhsa_user_sgpr_queue_ptr 0
		.amdhsa_user_sgpr_kernarg_segment_ptr 1
		.amdhsa_user_sgpr_dispatch_id 0
		.amdhsa_user_sgpr_kernarg_preload_length 0
		.amdhsa_user_sgpr_kernarg_preload_offset 0
		.amdhsa_user_sgpr_private_segment_size 0
		.amdhsa_uses_dynamic_stack 0
		.amdhsa_enable_private_segment 0
		.amdhsa_system_sgpr_workgroup_id_x 1
		.amdhsa_system_sgpr_workgroup_id_y 0
		.amdhsa_system_sgpr_workgroup_id_z 0
		.amdhsa_system_sgpr_workgroup_info 0
		.amdhsa_system_vgpr_workitem_id 0
		.amdhsa_next_free_vgpr 252
		.amdhsa_next_free_sgpr 102
		.amdhsa_accum_offset 252
		.amdhsa_reserve_vcc 1
		.amdhsa_float_round_mode_32 0
		.amdhsa_float_round_mode_16_64 0
		.amdhsa_float_denorm_mode_32 3
		.amdhsa_float_denorm_mode_16_64 3
		.amdhsa_dx10_clamp 1
		.amdhsa_ieee_mode 1
		.amdhsa_fp16_overflow 0
		.amdhsa_tg_split 0
		.amdhsa_exception_fp_ieee_invalid_op 0
		.amdhsa_exception_fp_denorm_src 0
		.amdhsa_exception_fp_ieee_div_zero 0
		.amdhsa_exception_fp_ieee_overflow 0
		.amdhsa_exception_fp_ieee_underflow 0
		.amdhsa_exception_fp_ieee_inexact 0
		.amdhsa_exception_int_div_zero 0
	.end_amdhsa_kernel

; __global__ void __launch_bounds__(NWAVES * 64, 2) fwd(Args a) {
amdhsa.kernels:
  - .agpr_count:     0
    .args:
      - .offset:         0
        .size:           240
        .value_kind:     by_value
      - .offset:         240
        .size:           4
        .value_kind:     hidden_block_count_x
      - .offset:         244
        .size:           4
        .value_kind:     hidden_block_count_y
      - .offset:         248
        .size:           4
        .value_kind:     hidden_block_count_z
      - .offset:         252
        .size:           2
        .value_kind:     hidden_group_size_x
      - .offset:         254
        .size:           2
        .value_kind:     hidden_group_size_y
      - .offset:         256
        .size:           2
        .value_kind:     hidden_group_size_z
      - .offset:         258
        .size:           2
        .value_kind:     hidden_remainder_x
      - .offset:         260
        .size:           2
        .value_kind:     hidden_remainder_y
      - .offset:         262
        .size:           2
        .value_kind:     hidden_remainder_z
      - .offset:         280
        .size:           8
        .value_kind:     hidden_global_offset_x
      - .offset:         288
        .size:           8
        .value_kind:     hidden_global_offset_y
      - .offset:         296
        .size:           8
        .value_kind:     hidden_global_offset_z
      - .offset:         304
        .size:           2
        .value_kind:     hidden_grid_dims
      - .offset:         360
        .size:           4
        .value_kind:     hidden_dynamic_lds_size
    .group_segment_fixed_size: 0
    .kernarg_segment_align: 8
    .kernarg_segment_size: 496
    .language:       OpenCL C
    .language_version:
      - 2
      - 0
    .max_flat_workgroup_size: 512
    .name:           _Z3fwd4Args
    .private_segment_fixed_size: 0
    .sgpr_count:     108
    .sgpr_spill_count: 154
    .symbol:         _Z3fwd4Args.kd
    .uniform_work_group_size: 1
    .uses_dynamic_stack: false
    .vgpr_count:     252
    .vgpr_spill_count: 0
    .wavefront_size: 64
